# w_out/mlp2 tile prologue: wait only for the first k-tile's eight loads (vmcnt(16)) before the initial LDS fill; staging sets stay in flight
# baseline (speedup 1.0000x reference)
.LBB0_832:
	s_lshl_b32 s6, s57, 11
	s_and_b32 s6, s6, 0x1c0000
	s_add_u32 s10, s30, s6
	s_addc_u32 s11, s31, 0
	s_lshr_b32 s18, s58, 3
	s_lshl_b32 s6, s18, 7
	s_add_i32 s6, s35, s6
	s_lshl_b64 s[8:9], s[6:7], 11
	s_add_u32 s12, s30, s8
	s_addc_u32 s13, s31, s9
	s_lshl_b32 s8, s58, 7
	s_and_b32 s59, s8, 0x380
	s_mov_b64 s[8:9], s[30:31]
	v_mov_b32_e32 v0, v201
	s_add_i32 s18, s18, s25
	v_mbcnt_lo_u32_b32 v0, -1, v0
	v_mbcnt_hi_u32_b32 v0, -1, v0
	s_lshl_b32 s6, s18, 7
	v_add_u32_e32 v202, s33, v0
	s_lshl_b64 s[16:17], s[6:7], 11
	v_ashrrev_i32_e32 v44, 3, v202
	v_lshlrev_b32_e32 v0, 3, v202
	s_add_u32 s16, s14, s16
	v_and_b32_e32 v45, 56, v0
	v_lshlrev_b32_e32 v0, 11, v44
	s_addc_u32 s17, s15, s17
	v_lshl_or_b32 v200, v45, 1, v0
	v_lshl_add_u64 v[12:13], s[16:17], 0, v[200:201]
	v_add_co_u32_e32 v32, vcc, s37, v12
	s_lshl_b32 s19, s59, 11
	s_nop 0
	v_addc_co_u32_e32 v33, vcc, 0, v13, vcc
	v_add_co_u32_e32 v34, vcc, s38, v12
	s_add_u32 s20, s22, s19
	s_nop 0
	v_addc_co_u32_e32 v35, vcc, 0, v13, vcc
	v_add_co_u32_e32 v36, vcc, s39, v12
	s_addc_u32 s21, s23, 0
	s_nop 0
	v_addc_co_u32_e32 v37, vcc, 0, v13, vcc
	v_lshl_add_u64 v[28:29], s[20:21], 0, v[200:201]
	v_add_co_u32_e32 v38, vcc, s37, v28
	global_load_dwordx4 v[0:3], v200, s[16:17]
	global_load_dwordx4 v[16:19], v200, s[20:21]
	v_addc_co_u32_e32 v39, vcc, 0, v29, vcc
	v_add_co_u32_e32 v40, vcc, s38, v28
	global_load_dwordx4 v[4:7], v[32:33], off
	global_load_dwordx4 v[8:11], v[34:35], off
	v_addc_co_u32_e32 v41, vcc, 0, v29, vcc
	v_add_co_u32_e32 v42, vcc, s39, v28
	global_load_dwordx4 v[12:15], v[36:37], off
	global_load_dwordx4 v[20:23], v[38:39], off
	v_addc_co_u32_e32 v43, vcc, 0, v29, vcc
	global_load_dwordx4 v[24:27], v[40:41], off
	global_load_dwordx4 v[28:31], v[42:43], off
	global_load_dwordx4 v[64:67], v200, s[16:17] offset:128
	global_load_dwordx4 v[68:71], v[32:33], off offset:128
	global_load_dwordx4 v[72:75], v[34:35], off offset:128
	global_load_dwordx4 v[76:79], v[36:37], off offset:128
	global_load_dwordx4 v[88:91], v200, s[20:21] offset:128
	global_load_dwordx4 v[96:99], v[38:39], off offset:128
	global_load_dwordx4 v[104:107], v[40:41], off offset:128
	global_load_dwordx4 v[108:111], v[42:43], off offset:128
	s_waitcnt lgkmcnt(0)
	s_barrier
	global_load_dwordx4 v[84:87], v[32:33], off offset:256
	global_load_dwordx4 v[92:95], v[34:35], off offset:256
	global_load_dwordx4 v[80:83], v200, s[16:17] offset:256
	global_load_dwordx4 v[112:115], v200, s[20:21] offset:256
	global_load_dwordx4 v[100:103], v[36:37], off offset:256
	global_load_dwordx4 v[116:119], v[38:39], off offset:256
	global_load_dwordx4 v[120:123], v[40:41], off offset:256
	global_load_dwordx4 v[124:127], v[42:43], off offset:256
	v_mul_lo_u32 v44, v44, s36
	v_add_lshl_u32 v206, v44, v45, 1
	v_and_b32_e32 v203, 31, v202
	v_bfe_u32 v204, v202, 5, 1
	s_mov_b32 s19, 0
	s_waitcnt vmcnt(16)
	ds_write_b128 v206, v[0:3]
	ds_write_b128 v206, v[4:7] offset:4608
	ds_write_b128 v206, v[8:11] offset:9216
	ds_write_b128 v206, v[12:15] offset:13824
	ds_write_b128 v206, v[16:19] offset:18432
	ds_write_b128 v206, v[20:23] offset:23040
	ds_write_b128 v206, v[24:27] offset:27648
	ds_write_b128 v206, v[28:31] offset:32256
	v_ashrrev_i32_e32 v0, 1, v202
	v_and_b32_e32 v205, 0xffffffc0, v0
	v_or_b32_e32 v0, v205, v203
	v_and_b32_e32 v2, 0x5f, v202
	v_lshlrev_b32_e32 v1, 4, v204
	v_mul_u32_u24_e32 v2, 0x90, v2
	v_mul_lo_u32 v3, v0, s40
	v_mov_b32_e32 v0, 0
	v_add_u32_e32 v207, v1, v3
	v_add_u32_e32 v208, v1, v2
	v_mov_b32_e32 v1, v0
	v_mov_b32_e32 v2, v0
	v_mov_b32_e32 v3, v0
	v_mov_b32_e32 v4, v0
	v_mov_b32_e32 v5, v0
	v_mov_b32_e32 v6, v0
	v_mov_b32_e32 v7, v0
	v_mov_b32_e32 v8, v0
	v_mov_b32_e32 v9, v0
	v_mov_b32_e32 v10, v0
	v_mov_b32_e32 v11, v0
	v_mov_b32_e32 v12, v0
	v_mov_b32_e32 v13, v0
	v_mov_b32_e32 v14, v0
	v_mov_b32_e32 v15, v0
	v_mov_b32_e32 v32, v0
	v_mov_b32_e32 v33, v0
	v_mov_b32_e32 v34, v0
	v_mov_b32_e32 v35, v0
	v_mov_b32_e32 v36, v0
	v_mov_b32_e32 v37, v0
	v_mov_b32_e32 v38, v0
	v_mov_b32_e32 v39, v0
	v_mov_b32_e32 v40, v0
	v_mov_b32_e32 v41, v0
	v_mov_b32_e32 v42, v0
	v_mov_b32_e32 v43, v0
	v_mov_b32_e32 v44, v0
	v_mov_b32_e32 v45, v0
	v_mov_b32_e32 v46, v0
	v_mov_b32_e32 v47, v0
	v_mov_b32_e32 v16, v0
	v_mov_b32_e32 v17, v0
	v_mov_b32_e32 v18, v0
	v_mov_b32_e32 v19, v0
	v_mov_b32_e32 v20, v0
	v_mov_b32_e32 v21, v0
	v_mov_b32_e32 v22, v0
	v_mov_b32_e32 v23, v0
	v_mov_b32_e32 v24, v0
	v_mov_b32_e32 v25, v0
	v_mov_b32_e32 v26, v0
	v_mov_b32_e32 v27, v0
	v_mov_b32_e32 v28, v0
	v_mov_b32_e32 v29, v0
	v_mov_b32_e32 v30, v0
	v_mov_b32_e32 v31, v0
	v_mov_b32_e32 v48, v0
	v_mov_b32_e32 v49, v0
	v_mov_b32_e32 v50, v0
	v_mov_b32_e32 v51, v0
	v_mov_b32_e32 v52, v0
	v_mov_b32_e32 v53, v0
	v_mov_b32_e32 v54, v0
	v_mov_b32_e32 v55, v0
	v_mov_b32_e32 v56, v0
	v_mov_b32_e32 v57, v0
	v_mov_b32_e32 v58, v0
	v_mov_b32_e32 v59, v0
	v_mov_b32_e32 v60, v0
	v_mov_b32_e32 v61, v0
	v_mov_b32_e32 v62, v0
	v_mov_b32_e32 v63, v0
	s_waitcnt lgkmcnt(0)
	s_barrier
	s_branch .LBB0_834

.LBB0_1065:
	s_lshl_b32 s0, s60, 13
	s_and_b32 s0, s0, 0x700000
	s_add_u32 s10, s30, s0
	s_addc_u32 s11, s31, 0
	s_lshr_b32 s18, s61, 3
	s_lshl_b32 s0, s18, 7
	s_add_i32 s0, s37, s0
	s_lshl_b64 s[8:9], s[0:1], 13
	s_add_u32 s12, s30, s8
	s_addc_u32 s13, s31, s9
	s_lshl_b32 s8, s61, 7
	s_and_b32 s62, s8, 0x380
	s_mov_b64 s[8:9], s[30:31]
	v_mov_b32_e32 v0, v201
	s_add_i32 s18, s18, s25
	v_mbcnt_lo_u32_b32 v0, -1, v0
	v_mbcnt_hi_u32_b32 v0, -1, v0
	s_lshl_b32 s0, s18, 7
	v_add_u32_e32 v202, s33, v0
	s_lshl_b64 s[16:17], s[0:1], 13
	v_ashrrev_i32_e32 v44, 3, v202
	v_lshlrev_b32_e32 v0, 3, v202
	s_add_u32 s16, s26, s16
	v_and_b32_e32 v45, 56, v0
	v_lshlrev_b32_e32 v0, 13, v44
	s_addc_u32 s17, s27, s17
	v_lshl_or_b32 v200, v45, 1, v0
	v_lshl_add_u64 v[12:13], s[16:17], 0, v[200:201]
	v_add_co_u32_e32 v32, vcc, s39, v12
	s_lshl_b32 s19, s62, 13
	s_nop 0
	v_addc_co_u32_e32 v33, vcc, 0, v13, vcc
	v_add_co_u32_e32 v34, vcc, s40, v12
	s_add_u32 s20, s22, s19
	s_nop 0
	v_addc_co_u32_e32 v35, vcc, 0, v13, vcc
	v_add_co_u32_e32 v36, vcc, s41, v12
	s_addc_u32 s21, s23, 0
	s_nop 0
	v_addc_co_u32_e32 v37, vcc, 0, v13, vcc
	v_lshl_add_u64 v[28:29], s[20:21], 0, v[200:201]
	v_add_co_u32_e32 v38, vcc, s39, v28
	global_load_dwordx4 v[0:3], v200, s[16:17]
	global_load_dwordx4 v[16:19], v200, s[20:21]
	v_addc_co_u32_e32 v39, vcc, 0, v29, vcc
	v_add_co_u32_e32 v40, vcc, s40, v28
	global_load_dwordx4 v[4:7], v[32:33], off
	global_load_dwordx4 v[8:11], v[34:35], off
	v_addc_co_u32_e32 v41, vcc, 0, v29, vcc
	v_add_co_u32_e32 v42, vcc, s41, v28
	global_load_dwordx4 v[12:15], v[36:37], off
	global_load_dwordx4 v[20:23], v[38:39], off
	v_addc_co_u32_e32 v43, vcc, 0, v29, vcc
	global_load_dwordx4 v[24:27], v[40:41], off
	global_load_dwordx4 v[28:31], v[42:43], off
	global_load_dwordx4 v[64:67], v200, s[16:17] offset:128
	global_load_dwordx4 v[68:71], v[32:33], off offset:128
	global_load_dwordx4 v[72:75], v[34:35], off offset:128
	global_load_dwordx4 v[76:79], v[36:37], off offset:128
	global_load_dwordx4 v[88:91], v200, s[20:21] offset:128
	global_load_dwordx4 v[96:99], v[38:39], off offset:128
	global_load_dwordx4 v[104:107], v[40:41], off offset:128
	global_load_dwordx4 v[108:111], v[42:43], off offset:128
	s_waitcnt lgkmcnt(0)
	s_barrier
	global_load_dwordx4 v[84:87], v[32:33], off offset:256
	global_load_dwordx4 v[92:95], v[34:35], off offset:256
	global_load_dwordx4 v[80:83], v200, s[16:17] offset:256
	global_load_dwordx4 v[112:115], v200, s[20:21] offset:256
	global_load_dwordx4 v[100:103], v[36:37], off offset:256
	global_load_dwordx4 v[116:119], v[38:39], off offset:256
	global_load_dwordx4 v[120:123], v[40:41], off offset:256
	global_load_dwordx4 v[124:127], v[42:43], off offset:256
	v_mul_lo_u32 v44, v44, s38
	v_add_lshl_u32 v206, v44, v45, 1
	v_and_b32_e32 v203, 31, v202
	v_bfe_u32 v204, v202, 5, 1
	s_mov_b32 s19, 0
	s_waitcnt vmcnt(16)
	ds_write_b128 v206, v[0:3]
	ds_write_b128 v206, v[4:7] offset:4608
	ds_write_b128 v206, v[8:11] offset:9216
	ds_write_b128 v206, v[12:15] offset:13824
	ds_write_b128 v206, v[16:19] offset:18432
	ds_write_b128 v206, v[20:23] offset:23040
	ds_write_b128 v206, v[24:27] offset:27648
	ds_write_b128 v206, v[28:31] offset:32256
	v_ashrrev_i32_e32 v0, 1, v202
	v_and_b32_e32 v205, 0xffffffc0, v0
	v_or_b32_e32 v0, v205, v203
	v_and_b32_e32 v2, 0x5f, v202
	v_lshlrev_b32_e32 v1, 4, v204
	v_mul_u32_u24_e32 v2, 0x90, v2
	v_mul_lo_u32 v3, v0, s42
	v_mov_b32_e32 v0, 0
	v_add_u32_e32 v207, v1, v3
	v_add_u32_e32 v208, v1, v2
	v_mov_b32_e32 v1, v0
	v_mov_b32_e32 v2, v0
	v_mov_b32_e32 v3, v0
	v_mov_b32_e32 v4, v0
	v_mov_b32_e32 v5, v0
	v_mov_b32_e32 v6, v0
	v_mov_b32_e32 v7, v0
	v_mov_b32_e32 v8, v0
	v_mov_b32_e32 v9, v0
	v_mov_b32_e32 v10, v0
	v_mov_b32_e32 v11, v0
	v_mov_b32_e32 v12, v0
	v_mov_b32_e32 v13, v0
	v_mov_b32_e32 v14, v0
	v_mov_b32_e32 v15, v0
	v_mov_b32_e32 v32, v0
	v_mov_b32_e32 v33, v0
	v_mov_b32_e32 v34, v0
	v_mov_b32_e32 v35, v0
	v_mov_b32_e32 v36, v0
	v_mov_b32_e32 v37, v0
	v_mov_b32_e32 v38, v0
	v_mov_b32_e32 v39, v0
	v_mov_b32_e32 v40, v0
	v_mov_b32_e32 v41, v0
	v_mov_b32_e32 v42, v0
	v_mov_b32_e32 v43, v0
	v_mov_b32_e32 v44, v0
	v_mov_b32_e32 v45, v0
	v_mov_b32_e32 v46, v0
	v_mov_b32_e32 v47, v0
	v_mov_b32_e32 v16, v0
	v_mov_b32_e32 v17, v0
	v_mov_b32_e32 v18, v0
	v_mov_b32_e32 v19, v0
	v_mov_b32_e32 v20, v0
	v_mov_b32_e32 v21, v0
	v_mov_b32_e32 v22, v0
	v_mov_b32_e32 v23, v0
	v_mov_b32_e32 v24, v0
	v_mov_b32_e32 v25, v0
	v_mov_b32_e32 v26, v0
	v_mov_b32_e32 v27, v0
	v_mov_b32_e32 v28, v0
	v_mov_b32_e32 v29, v0
	v_mov_b32_e32 v30, v0
	v_mov_b32_e32 v31, v0
	v_mov_b32_e32 v48, v0
	v_mov_b32_e32 v49, v0
	v_mov_b32_e32 v50, v0
	v_mov_b32_e32 v51, v0
	v_mov_b32_e32 v52, v0
	v_mov_b32_e32 v53, v0
	v_mov_b32_e32 v54, v0
	v_mov_b32_e32 v55, v0
	v_mov_b32_e32 v56, v0
	v_mov_b32_e32 v57, v0
	v_mov_b32_e32 v58, v0
	v_mov_b32_e32 v59, v0
	v_mov_b32_e32 v60, v0
	v_mov_b32_e32 v61, v0
	v_mov_b32_e32 v62, v0
	v_mov_b32_e32 v63, v0
	s_waitcnt lgkmcnt(0)
	s_barrier
	s_branch .LBB0_1067

.LBB0_1812:
	s_lshl_b32 s6, s56, 11
	s_and_b32 s6, s6, 0x1c0000
	s_add_u32 s10, s30, s6
	s_addc_u32 s11, s31, 0
	s_lshr_b32 s6, s57, 3
	s_add_i32 s6, s25, s6
	s_lshr_b32 s6, s6, 4
	s_mul_i32 s6, s6, 18
	s_bfe_u32 s8, s57, 0x40003
	s_add_i32 s18, s6, s8
	s_add_i32 s18, s18, 2
	s_lshl_b32 s6, s18, 7
	s_lshl_b64 s[16:17], s[6:7], 11
	s_add_u32 s12, s30, s16
	s_addc_u32 s13, s31, s17
	s_lshl_b32 s8, s57, 7
	s_and_b32 s58, s8, 0x380
	s_mov_b64 s[8:9], s[30:31]
	v_mov_b32_e32 v0, v201
	s_add_u32 s16, s14, s16
	v_mbcnt_lo_u32_b32 v0, -1, v0
	v_mbcnt_hi_u32_b32 v0, -1, v0
	v_add_u32_e32 v202, s33, v0
	s_addc_u32 s17, s15, s17
	v_ashrrev_i32_e32 v44, 3, v202
	v_lshlrev_b32_e32 v0, 3, v202
	v_and_b32_e32 v45, 56, v0
	v_lshlrev_b32_e32 v0, 11, v44
	v_lshl_or_b32 v200, v45, 1, v0
	v_lshl_add_u64 v[12:13], s[16:17], 0, v[200:201]
	v_add_co_u32_e32 v32, vcc, s36, v12
	s_lshl_b32 s19, s58, 11
	s_nop 0
	v_addc_co_u32_e32 v33, vcc, 0, v13, vcc
	v_add_co_u32_e32 v34, vcc, s37, v12
	s_add_u32 s20, s22, s19
	s_nop 0
	v_addc_co_u32_e32 v35, vcc, 0, v13, vcc
	v_add_co_u32_e32 v36, vcc, s38, v12
	s_addc_u32 s21, s23, 0
	s_nop 0
	v_addc_co_u32_e32 v37, vcc, 0, v13, vcc
	v_lshl_add_u64 v[28:29], s[20:21], 0, v[200:201]
	v_add_co_u32_e32 v38, vcc, s36, v28
	global_load_dwordx4 v[0:3], v200, s[16:17]
	global_load_dwordx4 v[16:19], v200, s[20:21]
	v_addc_co_u32_e32 v39, vcc, 0, v29, vcc
	v_add_co_u32_e32 v40, vcc, s37, v28
	global_load_dwordx4 v[4:7], v[32:33], off
	global_load_dwordx4 v[8:11], v[34:35], off
	v_addc_co_u32_e32 v41, vcc, 0, v29, vcc
	v_add_co_u32_e32 v42, vcc, s38, v28
	global_load_dwordx4 v[12:15], v[36:37], off
	global_load_dwordx4 v[20:23], v[38:39], off
	v_addc_co_u32_e32 v43, vcc, 0, v29, vcc
	global_load_dwordx4 v[24:27], v[40:41], off
	global_load_dwordx4 v[28:31], v[42:43], off
	global_load_dwordx4 v[64:67], v200, s[16:17] offset:128
	global_load_dwordx4 v[68:71], v[32:33], off offset:128
	global_load_dwordx4 v[72:75], v[34:35], off offset:128
	global_load_dwordx4 v[76:79], v[36:37], off offset:128
	global_load_dwordx4 v[88:91], v200, s[20:21] offset:128
	global_load_dwordx4 v[96:99], v[38:39], off offset:128
	global_load_dwordx4 v[104:107], v[40:41], off offset:128
	global_load_dwordx4 v[108:111], v[42:43], off offset:128
	s_waitcnt lgkmcnt(0)
	s_barrier
	global_load_dwordx4 v[84:87], v[32:33], off offset:256
	global_load_dwordx4 v[92:95], v[34:35], off offset:256
	global_load_dwordx4 v[80:83], v200, s[16:17] offset:256
	global_load_dwordx4 v[112:115], v200, s[20:21] offset:256
	global_load_dwordx4 v[100:103], v[36:37], off offset:256
	global_load_dwordx4 v[116:119], v[38:39], off offset:256
	global_load_dwordx4 v[120:123], v[40:41], off offset:256
	global_load_dwordx4 v[124:127], v[42:43], off offset:256
	v_mul_lo_u32 v44, v44, s35
	v_add_lshl_u32 v206, v44, v45, 1
	v_and_b32_e32 v203, 31, v202
	v_bfe_u32 v204, v202, 5, 1
	s_mov_b32 s19, 0
	s_waitcnt vmcnt(16)
	ds_write_b128 v206, v[0:3]
	ds_write_b128 v206, v[4:7] offset:4608
	ds_write_b128 v206, v[8:11] offset:9216
	ds_write_b128 v206, v[12:15] offset:13824
	ds_write_b128 v206, v[16:19] offset:18432
	ds_write_b128 v206, v[20:23] offset:23040
	ds_write_b128 v206, v[24:27] offset:27648
	ds_write_b128 v206, v[28:31] offset:32256
	v_ashrrev_i32_e32 v0, 1, v202
	v_and_b32_e32 v205, 0xffffffc0, v0
	v_or_b32_e32 v0, v205, v203
	v_and_b32_e32 v2, 0x5f, v202
	v_lshlrev_b32_e32 v1, 4, v204
	v_mul_u32_u24_e32 v2, 0x90, v2
	v_mul_lo_u32 v3, v0, s39
	v_mov_b32_e32 v0, 0
	v_add_u32_e32 v207, v1, v3
	v_add_u32_e32 v208, v1, v2
	v_mov_b32_e32 v1, v0
	v_mov_b32_e32 v2, v0
	v_mov_b32_e32 v3, v0
	v_mov_b32_e32 v4, v0
	v_mov_b32_e32 v5, v0
	v_mov_b32_e32 v6, v0
	v_mov_b32_e32 v7, v0
	v_mov_b32_e32 v8, v0
	v_mov_b32_e32 v9, v0
	v_mov_b32_e32 v10, v0
	v_mov_b32_e32 v11, v0
	v_mov_b32_e32 v12, v0
	v_mov_b32_e32 v13, v0
	v_mov_b32_e32 v14, v0
	v_mov_b32_e32 v15, v0
	v_mov_b32_e32 v32, v0
	v_mov_b32_e32 v33, v0
	v_mov_b32_e32 v34, v0
	v_mov_b32_e32 v35, v0
	v_mov_b32_e32 v36, v0
	v_mov_b32_e32 v37, v0
	v_mov_b32_e32 v38, v0
	v_mov_b32_e32 v39, v0
	v_mov_b32_e32 v40, v0
	v_mov_b32_e32 v41, v0
	v_mov_b32_e32 v42, v0
	v_mov_b32_e32 v43, v0
	v_mov_b32_e32 v44, v0
	v_mov_b32_e32 v45, v0
	v_mov_b32_e32 v46, v0
	v_mov_b32_e32 v47, v0
	v_mov_b32_e32 v16, v0
	v_mov_b32_e32 v17, v0
	v_mov_b32_e32 v18, v0
	v_mov_b32_e32 v19, v0
	v_mov_b32_e32 v20, v0
	v_mov_b32_e32 v21, v0
	v_mov_b32_e32 v22, v0
	v_mov_b32_e32 v23, v0
	v_mov_b32_e32 v24, v0
	v_mov_b32_e32 v25, v0
	v_mov_b32_e32 v26, v0
	v_mov_b32_e32 v27, v0
	v_mov_b32_e32 v28, v0
	v_mov_b32_e32 v29, v0
	v_mov_b32_e32 v30, v0
	v_mov_b32_e32 v31, v0
	v_mov_b32_e32 v48, v0
	v_mov_b32_e32 v49, v0
	v_mov_b32_e32 v50, v0
	v_mov_b32_e32 v51, v0
	v_mov_b32_e32 v52, v0
	v_mov_b32_e32 v53, v0
	v_mov_b32_e32 v54, v0
	v_mov_b32_e32 v55, v0
	v_mov_b32_e32 v56, v0
	v_mov_b32_e32 v57, v0
	v_mov_b32_e32 v58, v0
	v_mov_b32_e32 v59, v0
	v_mov_b32_e32 v60, v0
	v_mov_b32_e32 v61, v0
	v_mov_b32_e32 v62, v0
	v_mov_b32_e32 v63, v0
	s_waitcnt lgkmcnt(0)
	s_barrier
	s_branch .LBB0_1814

.LBB0_2045:
	s_lshl_b32 s0, s57, 13
	s_and_b32 s0, s0, 0x700000
	s_add_u32 s10, s30, s0
	s_addc_u32 s11, s31, 0
	s_lshr_b32 s0, s58, 3
	s_add_i32 s0, s23, s0
	s_lshr_b32 s0, s0, 4
	s_mul_i32 s0, s0, 18
	s_bfe_u32 s8, s58, 0x40003
	s_add_i32 s16, s0, s8
	s_add_i32 s16, s16, 2
	s_lshl_b32 s0, s16, 7
	s_lshl_b64 s[14:15], s[0:1], 13
	s_add_u32 s12, s30, s14
	s_addc_u32 s13, s31, s15
	s_lshl_b32 s8, s58, 7
	s_and_b32 s59, s8, 0x380
	s_mov_b64 s[8:9], s[30:31]
	v_mov_b32_e32 v0, v201
	s_add_u32 s14, s24, s14
	v_mbcnt_lo_u32_b32 v0, -1, v0
	v_mbcnt_hi_u32_b32 v0, -1, v0
	v_add_u32_e32 v202, s33, v0
	s_addc_u32 s15, s25, s15
	v_ashrrev_i32_e32 v44, 3, v202
	v_lshlrev_b32_e32 v0, 3, v202
	v_and_b32_e32 v45, 56, v0
	v_lshlrev_b32_e32 v0, 13, v44
	v_lshl_or_b32 v200, v45, 1, v0
	v_lshl_add_u64 v[12:13], s[14:15], 0, v[200:201]
	v_add_co_u32_e32 v32, vcc, s36, v12
	s_lshl_b32 s17, s59, 13
	s_nop 0
	v_addc_co_u32_e32 v33, vcc, 0, v13, vcc
	v_add_co_u32_e32 v34, vcc, s37, v12
	s_add_u32 s18, s20, s17
	s_nop 0
	v_addc_co_u32_e32 v35, vcc, 0, v13, vcc
	v_add_co_u32_e32 v36, vcc, s38, v12
	s_addc_u32 s19, s21, 0
	s_nop 0
	v_addc_co_u32_e32 v37, vcc, 0, v13, vcc
	v_lshl_add_u64 v[28:29], s[18:19], 0, v[200:201]
	v_add_co_u32_e32 v38, vcc, s36, v28
	global_load_dwordx4 v[0:3], v200, s[14:15]
	global_load_dwordx4 v[16:19], v200, s[18:19]
	v_addc_co_u32_e32 v39, vcc, 0, v29, vcc
	v_add_co_u32_e32 v40, vcc, s37, v28
	global_load_dwordx4 v[4:7], v[32:33], off
	global_load_dwordx4 v[8:11], v[34:35], off
	v_addc_co_u32_e32 v41, vcc, 0, v29, vcc
	v_add_co_u32_e32 v42, vcc, s38, v28
	global_load_dwordx4 v[12:15], v[36:37], off
	global_load_dwordx4 v[20:23], v[38:39], off
	v_addc_co_u32_e32 v43, vcc, 0, v29, vcc
	global_load_dwordx4 v[24:27], v[40:41], off
	global_load_dwordx4 v[28:31], v[42:43], off
	global_load_dwordx4 v[64:67], v200, s[14:15] offset:128
	global_load_dwordx4 v[68:71], v[32:33], off offset:128
	global_load_dwordx4 v[72:75], v[34:35], off offset:128
	global_load_dwordx4 v[76:79], v[36:37], off offset:128
	global_load_dwordx4 v[88:91], v200, s[18:19] offset:128
	global_load_dwordx4 v[96:99], v[38:39], off offset:128
	global_load_dwordx4 v[104:107], v[40:41], off offset:128
	global_load_dwordx4 v[108:111], v[42:43], off offset:128
	s_waitcnt lgkmcnt(0)
	s_barrier
	global_load_dwordx4 v[84:87], v[32:33], off offset:256
	global_load_dwordx4 v[92:95], v[34:35], off offset:256
	global_load_dwordx4 v[80:83], v200, s[14:15] offset:256
	global_load_dwordx4 v[112:115], v200, s[18:19] offset:256
	global_load_dwordx4 v[100:103], v[36:37], off offset:256
	global_load_dwordx4 v[116:119], v[38:39], off offset:256
	global_load_dwordx4 v[120:123], v[40:41], off offset:256
	global_load_dwordx4 v[124:127], v[42:43], off offset:256
	v_mul_lo_u32 v44, v44, s35
	v_add_lshl_u32 v206, v44, v45, 1
	v_and_b32_e32 v203, 31, v202
	v_bfe_u32 v204, v202, 5, 1
	s_mov_b32 s17, 0
	s_waitcnt vmcnt(16)
	ds_write_b128 v206, v[0:3]
	ds_write_b128 v206, v[4:7] offset:4608
	ds_write_b128 v206, v[8:11] offset:9216
	ds_write_b128 v206, v[12:15] offset:13824
	ds_write_b128 v206, v[16:19] offset:18432
	ds_write_b128 v206, v[20:23] offset:23040
	ds_write_b128 v206, v[24:27] offset:27648
	ds_write_b128 v206, v[28:31] offset:32256
	v_ashrrev_i32_e32 v0, 1, v202
	v_and_b32_e32 v205, 0xffffffc0, v0
	v_or_b32_e32 v0, v205, v203
	v_and_b32_e32 v2, 0x5f, v202
	v_lshlrev_b32_e32 v1, 4, v204
	v_mul_u32_u24_e32 v2, 0x90, v2
	v_mul_lo_u32 v3, v0, s39
	v_mov_b32_e32 v0, 0
	v_add_u32_e32 v207, v1, v3
	v_add_u32_e32 v208, v1, v2
	v_mov_b32_e32 v1, v0
	v_mov_b32_e32 v2, v0
	v_mov_b32_e32 v3, v0
	v_mov_b32_e32 v4, v0
	v_mov_b32_e32 v5, v0
	v_mov_b32_e32 v6, v0
	v_mov_b32_e32 v7, v0
	v_mov_b32_e32 v8, v0
	v_mov_b32_e32 v9, v0
	v_mov_b32_e32 v10, v0
	v_mov_b32_e32 v11, v0
	v_mov_b32_e32 v12, v0
	v_mov_b32_e32 v13, v0
	v_mov_b32_e32 v14, v0
	v_mov_b32_e32 v15, v0
	v_mov_b32_e32 v32, v0
	v_mov_b32_e32 v33, v0
	v_mov_b32_e32 v34, v0
	v_mov_b32_e32 v35, v0
	v_mov_b32_e32 v36, v0
	v_mov_b32_e32 v37, v0
	v_mov_b32_e32 v38, v0
	v_mov_b32_e32 v39, v0
	v_mov_b32_e32 v40, v0
	v_mov_b32_e32 v41, v0
	v_mov_b32_e32 v42, v0
	v_mov_b32_e32 v43, v0
	v_mov_b32_e32 v44, v0
	v_mov_b32_e32 v45, v0
	v_mov_b32_e32 v46, v0
	v_mov_b32_e32 v47, v0
	v_mov_b32_e32 v16, v0
	v_mov_b32_e32 v17, v0
	v_mov_b32_e32 v18, v0
	v_mov_b32_e32 v19, v0
	v_mov_b32_e32 v20, v0
	v_mov_b32_e32 v21, v0
	v_mov_b32_e32 v22, v0
	v_mov_b32_e32 v23, v0
	v_mov_b32_e32 v24, v0
	v_mov_b32_e32 v25, v0
	v_mov_b32_e32 v26, v0
	v_mov_b32_e32 v27, v0
	v_mov_b32_e32 v28, v0
	v_mov_b32_e32 v29, v0
	v_mov_b32_e32 v30, v0
	v_mov_b32_e32 v31, v0
	v_mov_b32_e32 v48, v0
	v_mov_b32_e32 v49, v0
	v_mov_b32_e32 v50, v0
	v_mov_b32_e32 v51, v0
	v_mov_b32_e32 v52, v0
	v_mov_b32_e32 v53, v0
	v_mov_b32_e32 v54, v0
	v_mov_b32_e32 v55, v0
	v_mov_b32_e32 v56, v0
	v_mov_b32_e32 v57, v0
	v_mov_b32_e32 v58, v0
	v_mov_b32_e32 v59, v0
	v_mov_b32_e32 v60, v0
	v_mov_b32_e32 v61, v0
	v_mov_b32_e32 v62, v0
	v_mov_b32_e32 v63, v0
	s_waitcnt lgkmcnt(0)
	s_barrier
	s_branch .LBB0_2047
